# opt29: at the grid barrier a non-leader workgroup issues its L1 invalidate (buffer_inv sc1) when it starts waiting (it only polls with L1-bypassing sc1 loads until released) instead of after the relea
# speedup vs baseline: 1.0327x; 1.0327x over previous
.LBB0_152:
	s_or_b64 exec, exec, s[8:9]
	v_cvt_f32_u32_e32 v4, v2
	s_waitcnt vmcnt(0)
	v_readfirstlane_b32 s3, v3
	v_sub_u32_e32 v3, 0, v2
	v_rcp_iflag_f32_e32 v4, v4
	v_add_u32_e32 v5, s3, v1
	v_mul_f32_e32 v4, 0x4f7ffffe, v4
	v_cvt_u32_f32_e32 v4, v4
	v_mul_lo_u32 v1, v3, v4
	v_mul_hi_u32 v1, v4, v1
	v_add_u32_e32 v1, v4, v1
	v_mul_hi_u32 v1, v5, v1
	v_mul_lo_u32 v3, v1, v2
	v_sub_u32_e32 v3, v5, v3
	v_add_u32_e32 v4, 1, v1
	v_cmp_ge_u32_e32 vcc, v3, v2
	s_nop 1
	v_cndmask_b32_e32 v1, v1, v4, vcc
	v_sub_u32_e32 v4, v3, v2
	v_cndmask_b32_e32 v3, v3, v4, vcc
	v_add_u32_e32 v4, 1, v1
	v_cmp_ge_u32_e32 vcc, v3, v2
	v_add_u32_e32 v3, 1, v5
	s_nop 0
	v_cndmask_b32_e32 v1, v1, v4, vcc
	v_mul_lo_u32 v4, v2, v1
	v_add_u32_e32 v2, v4, v2
	v_cmp_ne_u32_e32 vcc, v3, v2
	s_and_saveexec_b64 s[6:7], vcc
	s_xor_b64 s[6:7], exec, s[6:7]
	s_cbranch_execz .LBB0_166
	buffer_inv sc1
	s_waitcnt lgkmcnt(0)
	v_mov_b32_e32 v0, 0x2000
	global_load_dword v0, v0, s[4:5] offset:1024 sc1
	s_add_u32 s14, s4, 0x2400
	s_addc_u32 s15, s5, 0
	s_waitcnt vmcnt(0)
	v_cmp_eq_u32_e32 vcc, v0, v1
	s_and_saveexec_b64 s[8:9], vcc
	s_cbranch_execz .LBB0_165
	s_add_u32 s10, s70, 0x4200
	s_addc_u32 s11, s71, 0
	s_mov_b32 s3, 1
	s_mov_b64 s[16:17], 0
	v_mov_b32_e32 v0, 0
	s_branch .LBB0_156

.LBB0_165:
	s_or_b64 exec, exec, s[8:9]
	s_waitcnt vmcnt(0)
	s_waitcnt vmcnt(0)

.LBB0_268:
	s_or_b64 exec, exec, s[8:9]
	v_cvt_f32_u32_e32 v4, v2
	s_waitcnt vmcnt(0)
	v_readfirstlane_b32 s3, v3
	v_sub_u32_e32 v3, 0, v2
	v_rcp_iflag_f32_e32 v4, v4
	v_add_u32_e32 v5, s3, v1
	v_mul_f32_e32 v4, 0x4f7ffffe, v4
	v_cvt_u32_f32_e32 v4, v4
	v_mul_lo_u32 v1, v3, v4
	v_mul_hi_u32 v1, v4, v1
	v_add_u32_e32 v1, v4, v1
	v_mul_hi_u32 v1, v5, v1
	v_mul_lo_u32 v3, v1, v2
	v_sub_u32_e32 v3, v5, v3
	v_add_u32_e32 v4, 1, v1
	v_cmp_ge_u32_e32 vcc, v3, v2
	s_nop 1
	v_cndmask_b32_e32 v1, v1, v4, vcc
	v_sub_u32_e32 v4, v3, v2
	v_cndmask_b32_e32 v3, v3, v4, vcc
	v_add_u32_e32 v4, 1, v1
	v_cmp_ge_u32_e32 vcc, v3, v2
	v_add_u32_e32 v3, 1, v5
	s_nop 0
	v_cndmask_b32_e32 v1, v1, v4, vcc
	v_mul_lo_u32 v4, v2, v1
	v_add_u32_e32 v2, v4, v2
	v_cmp_ne_u32_e32 vcc, v3, v2
	s_and_saveexec_b64 s[6:7], vcc
	s_xor_b64 s[6:7], exec, s[6:7]
	s_cbranch_execz .LBB0_282
	buffer_inv sc1
	s_waitcnt lgkmcnt(0)
	v_mov_b32_e32 v0, 0x2000
	global_load_dword v0, v0, s[4:5] offset:1024 sc1
	s_add_u32 s20, s4, 0x2400
	s_addc_u32 s21, s5, 0
	s_waitcnt vmcnt(0)
	v_cmp_eq_u32_e32 vcc, v0, v1
	s_and_saveexec_b64 s[8:9], vcc
	s_cbranch_execz .LBB0_281
	s_add_u32 s10, s70, 0x4200
	s_addc_u32 s11, s71, 0
	s_mov_b32 s3, 1
	s_mov_b64 s[22:23], 0
	v_mov_b32_e32 v0, 0
	s_branch .LBB0_272

.LBB0_330:
	s_or_b64 exec, exec, s[8:9]
	v_cvt_f32_u32_e32 v4, v2
	s_waitcnt vmcnt(0)
	v_readfirstlane_b32 s3, v3
	v_sub_u32_e32 v3, 0, v2
	v_rcp_iflag_f32_e32 v4, v4
	v_add_u32_e32 v5, s3, v1
	v_mul_f32_e32 v4, 0x4f7ffffe, v4
	v_cvt_u32_f32_e32 v4, v4
	v_mul_lo_u32 v1, v3, v4
	v_mul_hi_u32 v1, v4, v1
	v_add_u32_e32 v1, v4, v1
	v_mul_hi_u32 v1, v5, v1
	v_mul_lo_u32 v3, v1, v2
	v_sub_u32_e32 v3, v5, v3
	v_add_u32_e32 v4, 1, v1
	v_cmp_ge_u32_e32 vcc, v3, v2
	s_nop 1
	v_cndmask_b32_e32 v1, v1, v4, vcc
	v_sub_u32_e32 v4, v3, v2
	v_cndmask_b32_e32 v3, v3, v4, vcc
	v_add_u32_e32 v4, 1, v1
	v_cmp_ge_u32_e32 vcc, v3, v2
	v_add_u32_e32 v3, 1, v5
	s_nop 0
	v_cndmask_b32_e32 v1, v1, v4, vcc
	v_mul_lo_u32 v4, v2, v1
	v_add_u32_e32 v2, v4, v2
	v_cmp_ne_u32_e32 vcc, v3, v2
	s_and_saveexec_b64 s[6:7], vcc
	s_xor_b64 s[6:7], exec, s[6:7]
	s_cbranch_execz .LBB0_344
	buffer_inv sc1
	s_waitcnt lgkmcnt(0)
	v_mov_b32_e32 v0, 0x2000
	global_load_dword v0, v0, s[4:5] offset:1024 sc1
	s_add_u32 s22, s4, 0x2400
	s_addc_u32 s23, s5, 0
	s_waitcnt vmcnt(0)
	v_cmp_eq_u32_e32 vcc, v0, v1
	s_and_saveexec_b64 s[8:9], vcc
	s_cbranch_execz .LBB0_343
	s_add_u32 s10, s70, 0x4200
	s_addc_u32 s11, s71, 0
	s_mov_b32 s3, 1
	s_mov_b64 s[26:27], 0
	v_mov_b32_e32 v0, 0
	s_branch .LBB0_334

.LBB0_1365:
	s_or_b64 exec, exec, s[10:11]
	v_cvt_f32_u32_e32 v4, v2
	s_waitcnt vmcnt(0)
	v_readfirstlane_b32 s3, v3
	v_sub_u32_e32 v3, 0, v2
	v_rcp_iflag_f32_e32 v4, v4
	v_add_u32_e32 v5, s3, v1
	v_mul_f32_e32 v4, 0x4f7ffffe, v4
	v_cvt_u32_f32_e32 v4, v4
	v_mul_lo_u32 v1, v3, v4
	v_mul_hi_u32 v1, v4, v1
	v_add_u32_e32 v1, v4, v1
	v_mul_hi_u32 v1, v5, v1
	v_mul_lo_u32 v3, v1, v2
	v_sub_u32_e32 v3, v5, v3
	v_add_u32_e32 v4, 1, v1
	v_cmp_ge_u32_e32 vcc, v3, v2
	s_nop 1
	v_cndmask_b32_e32 v1, v1, v4, vcc
	v_sub_u32_e32 v4, v3, v2
	v_cndmask_b32_e32 v3, v3, v4, vcc
	v_add_u32_e32 v4, 1, v1
	v_cmp_ge_u32_e32 vcc, v3, v2
	v_add_u32_e32 v3, 1, v5
	s_nop 0
	v_cndmask_b32_e32 v1, v1, v4, vcc
	v_mul_lo_u32 v4, v2, v1
	v_add_u32_e32 v2, v4, v2
	v_cmp_ne_u32_e32 vcc, v3, v2
	s_and_saveexec_b64 s[6:7], vcc
	s_xor_b64 s[6:7], exec, s[6:7]
	s_cbranch_execz .LBB0_1379
	buffer_inv sc1
	s_waitcnt lgkmcnt(0)
	v_mov_b32_e32 v0, 0x2000
	global_load_dword v0, v0, s[4:5] offset:1024 sc1
	s_add_u32 s26, s4, 0x2400
	s_addc_u32 s27, s5, 0
	s_waitcnt vmcnt(0)
	v_cmp_eq_u32_e32 vcc, v0, v1
	s_and_saveexec_b64 s[10:11], vcc
	s_cbranch_execz .LBB0_1378
	s_add_u32 s22, s70, 0x4200
	s_addc_u32 s23, s71, 0
	s_mov_b32 s3, 1
	s_mov_b64 s[28:29], 0
	v_mov_b32_e32 v0, 0
	s_branch .LBB0_1369

.LBB0_1378:
	s_or_b64 exec, exec, s[10:11]
	s_waitcnt vmcnt(0)
	s_waitcnt vmcnt(0)

.LBB0_1945:
	s_or_b64 exec, exec, s[8:9]
	v_cvt_f32_u32_e32 v4, v2
	s_waitcnt vmcnt(0)
	v_readfirstlane_b32 s3, v3
	v_sub_u32_e32 v3, 0, v2
	v_rcp_iflag_f32_e32 v4, v4
	v_add_u32_e32 v5, s3, v1
	v_mul_f32_e32 v4, 0x4f7ffffe, v4
	v_cvt_u32_f32_e32 v4, v4
	v_mul_lo_u32 v1, v3, v4
	v_mul_hi_u32 v1, v4, v1
	v_add_u32_e32 v1, v4, v1
	v_mul_hi_u32 v1, v5, v1
	v_mul_lo_u32 v3, v1, v2
	v_sub_u32_e32 v3, v5, v3
	v_add_u32_e32 v4, 1, v1
	v_cmp_ge_u32_e32 vcc, v3, v2
	s_nop 1
	v_cndmask_b32_e32 v1, v1, v4, vcc
	v_sub_u32_e32 v4, v3, v2
	v_cndmask_b32_e32 v3, v3, v4, vcc
	v_add_u32_e32 v4, 1, v1
	v_cmp_ge_u32_e32 vcc, v3, v2
	v_add_u32_e32 v3, 1, v5
	s_nop 0
	v_cndmask_b32_e32 v1, v1, v4, vcc
	v_mul_lo_u32 v4, v2, v1
	v_add_u32_e32 v2, v4, v2
	v_cmp_ne_u32_e32 vcc, v3, v2
	s_and_saveexec_b64 s[6:7], vcc
	s_xor_b64 s[6:7], exec, s[6:7]
	s_cbranch_execz .LBB0_1959
	buffer_inv sc1
	s_waitcnt lgkmcnt(0)
	v_mov_b32_e32 v0, 0x2000
	global_load_dword v0, v0, s[4:5] offset:1024 sc1
	s_add_u32 s22, s4, 0x2400
	s_addc_u32 s23, s5, 0
	s_waitcnt vmcnt(0)
	v_cmp_eq_u32_e32 vcc, v0, v1
	s_and_saveexec_b64 s[8:9], vcc
	s_cbranch_execz .LBB0_1958
	s_add_u32 s10, s70, 0x4200
	s_addc_u32 s11, s71, 0
	s_mov_b32 s3, 1
	s_mov_b64 s[24:25], 0
	v_mov_b32_e32 v0, 0
	s_branch .LBB0_1949

.LBB0_2117:
	s_or_b64 exec, exec, s[8:9]
	v_cvt_f32_u32_e32 v4, v2
	s_waitcnt vmcnt(0)
	v_readfirstlane_b32 s3, v3
	v_sub_u32_e32 v3, 0, v2
	v_rcp_iflag_f32_e32 v4, v4
	v_add_u32_e32 v5, s3, v1
	v_mul_f32_e32 v4, 0x4f7ffffe, v4
	v_cvt_u32_f32_e32 v4, v4
	v_mul_lo_u32 v1, v3, v4
	v_mul_hi_u32 v1, v4, v1
	v_add_u32_e32 v1, v4, v1
	v_mul_hi_u32 v1, v5, v1
	v_mul_lo_u32 v3, v1, v2
	v_sub_u32_e32 v3, v5, v3
	v_add_u32_e32 v4, 1, v1
	v_cmp_ge_u32_e32 vcc, v3, v2
	s_nop 1
	v_cndmask_b32_e32 v1, v1, v4, vcc
	v_sub_u32_e32 v4, v3, v2
	v_cndmask_b32_e32 v3, v3, v4, vcc
	v_add_u32_e32 v4, 1, v1
	v_cmp_ge_u32_e32 vcc, v3, v2
	v_add_u32_e32 v3, 1, v5
	s_nop 0
	v_cndmask_b32_e32 v1, v1, v4, vcc
	v_mul_lo_u32 v4, v2, v1
	v_add_u32_e32 v2, v4, v2
	v_cmp_ne_u32_e32 vcc, v3, v2
	s_and_saveexec_b64 s[6:7], vcc
	s_xor_b64 s[6:7], exec, s[6:7]
	s_cbranch_execz .LBB0_2131
	buffer_inv sc1
	s_waitcnt lgkmcnt(0)
	v_mov_b32_e32 v0, 0x2000
	global_load_dword v0, v0, s[4:5] offset:1024 sc1
	s_add_u32 s18, s4, 0x2400
	s_addc_u32 s19, s5, 0
	s_waitcnt vmcnt(0)
	v_cmp_eq_u32_e32 vcc, v0, v1
	s_and_saveexec_b64 s[8:9], vcc
	s_cbranch_execz .LBB0_2130
	s_add_u32 s10, s70, 0x4200
	s_addc_u32 s11, s71, 0
	s_mov_b32 s3, 1
	s_mov_b64 s[20:21], 0
	v_mov_b32_e32 v0, 0
	s_branch .LBB0_2121

.LBB0_2200:
	s_or_b64 exec, exec, s[6:7]
	v_cvt_f32_u32_e32 v4, v2
	s_waitcnt vmcnt(0)
	v_readfirstlane_b32 s4, v3
	v_sub_u32_e32 v3, 0, v2
	v_rcp_iflag_f32_e32 v4, v4
	v_add_u32_e32 v5, s4, v1
	v_mul_f32_e32 v4, 0x4f7ffffe, v4
	v_cvt_u32_f32_e32 v4, v4
	v_mul_lo_u32 v1, v3, v4
	v_mul_hi_u32 v1, v4, v1
	v_add_u32_e32 v1, v4, v1
	v_mul_hi_u32 v1, v5, v1
	v_mul_lo_u32 v3, v1, v2
	v_sub_u32_e32 v3, v5, v3
	v_add_u32_e32 v4, 1, v1
	v_cmp_ge_u32_e32 vcc, v3, v2
	s_nop 1
	v_cndmask_b32_e32 v1, v1, v4, vcc
	v_sub_u32_e32 v4, v3, v2
	v_cndmask_b32_e32 v3, v3, v4, vcc
	v_add_u32_e32 v4, 1, v1
	v_cmp_ge_u32_e32 vcc, v3, v2
	v_add_u32_e32 v3, 1, v5
	s_nop 0
	v_cndmask_b32_e32 v1, v1, v4, vcc
	v_mul_lo_u32 v4, v2, v1
	v_add_u32_e32 v2, v4, v2
	v_cmp_ne_u32_e32 vcc, v3, v2
	s_and_saveexec_b64 s[4:5], vcc
	s_xor_b64 s[4:5], exec, s[4:5]
	s_cbranch_execz .LBB0_2214
	buffer_inv sc1
	s_waitcnt lgkmcnt(0)
	v_mov_b32_e32 v0, 0x2000
	global_load_dword v0, v0, s[2:3] offset:1024 sc1
	s_add_u32 s10, s2, 0x2400
	s_addc_u32 s11, s3, 0
	s_waitcnt vmcnt(0)
	v_cmp_eq_u32_e32 vcc, v0, v1
	s_and_saveexec_b64 s[6:7], vcc
	s_cbranch_execz .LBB0_2213
	s_add_u32 s8, s70, 0x4200
	s_addc_u32 s9, s71, 0
	s_mov_b32 s22, 1
	s_mov_b64 s[12:13], 0
	v_mov_b32_e32 v0, 0
	s_branch .LBB0_2204

.LBB0_2213:
	s_or_b64 exec, exec, s[6:7]
	s_waitcnt vmcnt(0)
	s_waitcnt vmcnt(0)
